# EpiRes (Wo/down GEMM) epilogue: 16 residual-row loads hoisted and issued together via SGPR-base addressing, counted vmcnt
# speedup vs baseline: 1.0553x; 1.0028x over previous
.LBB0_882:
	v_and_b32_e32 v147, 64, v199
	v_xor_b32_e32 v0, 16, v199
	v_add_u32_e32 v147, 64, v147
	v_cmp_lt_i32_e32 vcc, v0, v147
	v_lshl_add_u32 v146, s22, 8, v139
	s_lshl_b32 s11, s24, 8
	v_cndmask_b32_e32 v0, v199, v0, vcc
	v_lshlrev_b32_e32 v153, 2, v0
	v_xor_b32_e32 v0, 32, v199
	s_ashr_i32 s12, s11, 31
	v_cmp_lt_i32_e32 vcc, v0, v147
	v_ashrrev_i32_e32 v147, 31, v146
	v_mov_b32_e32 v145, s12
	v_or_b32_e32 v144, s11, v138
	v_lshlrev_b64 v[148:149], 10, v[146:147]
	v_lshl_add_u64 v[148:149], v[148:149], 0, v[144:145]
	v_lshl_add_u64 v[148:149], v[148:149], 1, s[44:45]
	v_lshl_add_u32 v250, v146, 10, v144
	v_lshlrev_b32_e32 v250, 1, v250
	s_add_u32 s98, s44, 0x0
	s_addc_u32 s99, s45, 0
	global_load_dwordx4 v[186:189], v250, s[98:99]
	global_load_dwordx4 v[190:193], v250, s[98:99] offset:256
	s_add_u32 s100, s44, 0x8000
	s_addc_u32 s101, s45, 0
	global_load_dwordx4 v[200:203], v250, s[100:101]
	global_load_dwordx4 v[204:207], v250, s[100:101] offset:256
	s_add_u32 s98, s44, 0x10000
	s_addc_u32 s99, s45, 0
	global_load_dwordx4 v[208:211], v250, s[98:99]
	global_load_dwordx4 v[212:215], v250, s[98:99] offset:256
	s_add_u32 s100, s44, 0x18000
	s_addc_u32 s101, s45, 0
	global_load_dwordx4 v[216:219], v250, s[100:101]
	global_load_dwordx4 v[220:223], v250, s[100:101] offset:256
	s_add_u32 s98, s44, 0x40000
	s_addc_u32 s99, s45, 0
	global_load_dwordx4 v[224:227], v250, s[98:99]
	global_load_dwordx4 v[228:231], v250, s[98:99] offset:256
	s_add_u32 s100, s44, 0x48000
	s_addc_u32 s101, s45, 0
	global_load_dwordx4 v[232:235], v250, s[100:101]
	global_load_dwordx4 v[236:239], v250, s[100:101] offset:256
	s_add_u32 s98, s44, 0x50000
	s_addc_u32 s99, s45, 0
	global_load_dwordx4 v[240:243], v250, s[98:99]
	global_load_dwordx4 v[244:247], v250, s[98:99] offset:256
	v_cndmask_b32_e32 v0, v199, v0, vcc
	v_lshlrev_b32_e32 v152, 2, v0
	s_waitcnt vmcnt(13)
	v_lshlrev_b32_e32 v182, 16, v186
	v_and_b32_e32 v183, 0xffff0000, v186
	v_lshlrev_b32_e32 v154, 16, v187
	v_and_b32_e32 v155, 0xffff0000, v187
	v_lshlrev_b32_e32 v184, 16, v188
	v_and_b32_e32 v185, 0xffff0000, v188
	v_lshlrev_b32_e32 v156, 16, v189
	v_and_b32_e32 v157, 0xffff0000, v189
	v_pk_add_f32 v[128:129], v[128:129], v[154:155]
	v_pk_add_f32 v[126:127], v[126:127], v[182:183]
	v_pk_add_f32 v[154:155], v[124:125], v[156:157]
	v_pk_add_f32 v[156:157], v[122:123], v[184:185]
	v_cvt_pk_bf16_f32 v122, v126, v127
	v_cvt_pk_bf16_f32 v123, v128, v129
	v_cvt_pk_bf16_f32 v124, v156, v157
	v_cvt_pk_bf16_f32 v125, v154, v155
	global_store_dwordx4 v[148:149], v[122:125], off
	v_mul_f32_e32 v0, v127, v127
	v_fmac_f32_e32 v0, v126, v126
	v_mul_f32_e32 v122, v129, v129
	v_fmac_f32_e32 v122, v128, v128
	v_add_f32_e32 v0, v0, v122
	v_mul_f32_e32 v122, v157, v157
	v_fmac_f32_e32 v122, v156, v156
	v_add_f32_e32 v0, v122, v0
	v_mul_f32_e32 v122, v155, v155
	v_fmac_f32_e32 v122, v154, v154
	v_add_f32_e32 v0, v122, v0
	s_waitcnt vmcnt(13)
	v_lshlrev_b32_e32 v126, 16, v190
	v_and_b32_e32 v127, 0xffff0000, v190
	v_lshlrev_b32_e32 v122, 16, v191
	v_and_b32_e32 v123, 0xffff0000, v191
	v_lshlrev_b32_e32 v128, 16, v192
	v_and_b32_e32 v129, 0xffff0000, v192
	v_lshlrev_b32_e32 v124, 16, v193
	v_and_b32_e32 v125, 0xffff0000, v193
	v_pk_add_f32 v[120:121], v[120:121], v[122:123]
	v_pk_add_f32 v[118:119], v[118:119], v[126:127]
	v_pk_add_f32 v[122:123], v[116:117], v[124:125]
	v_pk_add_f32 v[124:125], v[114:115], v[128:129]
	v_cvt_pk_bf16_f32 v114, v118, v119
	v_cvt_pk_bf16_f32 v115, v120, v121
	v_cvt_pk_bf16_f32 v116, v124, v125
	v_cvt_pk_bf16_f32 v117, v122, v123
	global_store_dwordx4 v[148:149], v[114:117], off offset:256
	s_nop 1
	v_mul_f32_e32 v114, v119, v119
	v_mul_f32_e32 v115, v121, v121
	v_fmac_f32_e32 v114, v118, v118
	v_fmac_f32_e32 v115, v120, v120
	v_add_f32_e32 v114, v114, v115
	v_mul_f32_e32 v115, v125, v125
	v_fmac_f32_e32 v115, v124, v124
	v_add_f32_e32 v114, v115, v114
	v_mul_f32_e32 v115, v123, v123
	v_fmac_f32_e32 v115, v122, v122
	v_add_f32_e32 v114, v115, v114
	v_add_f32_e32 v0, v0, v114
	ds_bpermute_b32 v114, v153, v0
	s_waitcnt lgkmcnt(0)
	v_add_f32_e32 v0, v0, v114
	ds_bpermute_b32 v114, v152, v0
	s_and_saveexec_b64 s[22:23], s[2:3]
	s_cbranch_execz .LBB0_884
	s_waitcnt lgkmcnt(0)
	v_add_f32_e32 v0, v0, v114
	v_fma_f32 v0, v0, s82, 0.5
	v_cvt_u32_f32_e32 v0, v0
	v_lshl_add_u64 v[114:115], v[146:147], 3, s[80:81]
	global_atomic_add_x2 v[114:115], v[0:1], off
.LBB0_884:
	s_or_b64 exec, exec, s[22:23]
	s_add_u32 s100, s44, 0x58000
	s_addc_u32 s101, s45, 0
	global_load_dwordx4 v[186:189], v250, s[100:101]
	global_load_dwordx4 v[190:193], v250, s[100:101] offset:256
	s_waitcnt lgkmcnt(0)
	v_or_b32_e32 v114, 16, v146
	v_ashrrev_i32_e32 v115, 31, v114
	v_lshlrev_b64 v[116:117], 10, v[114:115]
	v_lshl_add_u64 v[116:117], v[116:117], 0, v[144:145]
	v_lshl_add_u64 v[120:121], v[116:117], 1, s[44:45]
	s_waitcnt vmcnt(16)
	v_lshlrev_b32_e32 v122, 16, v200
	v_and_b32_e32 v123, 0xffff0000, v200
	v_lshlrev_b32_e32 v116, 16, v201
	v_and_b32_e32 v117, 0xffff0000, v201
	v_lshlrev_b32_e32 v124, 16, v202
	v_and_b32_e32 v125, 0xffff0000, v202
	v_lshlrev_b32_e32 v118, 16, v203
	v_and_b32_e32 v119, 0xffff0000, v203
	v_pk_add_f32 v[112:113], v[112:113], v[116:117]
	v_pk_add_f32 v[110:111], v[110:111], v[122:123]
	v_pk_add_f32 v[116:117], v[108:109], v[118:119]
	v_pk_add_f32 v[118:119], v[106:107], v[124:125]
	v_cvt_pk_bf16_f32 v106, v110, v111
	v_cvt_pk_bf16_f32 v107, v112, v113
	v_cvt_pk_bf16_f32 v108, v118, v119
	v_cvt_pk_bf16_f32 v109, v116, v117
	global_store_dwordx4 v[120:121], v[106:109], off
	v_mul_f32_e32 v0, v111, v111
	v_fmac_f32_e32 v0, v110, v110
	v_mul_f32_e32 v106, v113, v113
	v_fmac_f32_e32 v106, v112, v112
	v_add_f32_e32 v0, v0, v106
	v_mul_f32_e32 v106, v119, v119
	v_fmac_f32_e32 v106, v118, v118
	v_add_f32_e32 v0, v106, v0
	v_mul_f32_e32 v106, v117, v117
	v_fmac_f32_e32 v106, v116, v116
	v_add_f32_e32 v0, v106, v0
	s_waitcnt vmcnt(16)
	v_lshlrev_b32_e32 v110, 16, v204
	v_and_b32_e32 v111, 0xffff0000, v204
	v_lshlrev_b32_e32 v106, 16, v205
	v_and_b32_e32 v107, 0xffff0000, v205
	v_lshlrev_b32_e32 v112, 16, v206
	v_and_b32_e32 v113, 0xffff0000, v206
	v_lshlrev_b32_e32 v108, 16, v207
	v_and_b32_e32 v109, 0xffff0000, v207
	v_pk_add_f32 v[104:105], v[104:105], v[106:107]
	v_pk_add_f32 v[102:103], v[102:103], v[110:111]
	v_pk_add_f32 v[106:107], v[100:101], v[108:109]
	v_pk_add_f32 v[108:109], v[98:99], v[112:113]
	v_cvt_pk_bf16_f32 v98, v102, v103
	v_cvt_pk_bf16_f32 v99, v104, v105
	v_cvt_pk_bf16_f32 v100, v108, v109
	v_cvt_pk_bf16_f32 v101, v106, v107
	global_store_dwordx4 v[120:121], v[98:101], off offset:256
	s_nop 1
	v_mul_f32_e32 v98, v103, v103
	v_mul_f32_e32 v99, v105, v105
	v_fmac_f32_e32 v98, v102, v102
	v_fmac_f32_e32 v99, v104, v104
	v_add_f32_e32 v98, v98, v99
	v_mul_f32_e32 v99, v109, v109
	v_fmac_f32_e32 v99, v108, v108
	v_add_f32_e32 v98, v99, v98
	v_mul_f32_e32 v99, v107, v107
	v_fmac_f32_e32 v99, v106, v106
	v_add_f32_e32 v98, v99, v98
	v_add_f32_e32 v0, v0, v98
	ds_bpermute_b32 v98, v153, v0
	s_waitcnt lgkmcnt(0)
	v_add_f32_e32 v0, v0, v98
	ds_bpermute_b32 v98, v152, v0
	s_and_saveexec_b64 s[22:23], s[2:3]
	s_cbranch_execz .LBB0_886
	s_waitcnt lgkmcnt(0)
	v_add_f32_e32 v0, v0, v98
	v_fma_f32 v0, v0, s82, 0.5
	v_cvt_u32_f32_e32 v0, v0
	v_lshl_add_u64 v[98:99], v[114:115], 3, s[80:81]
	global_atomic_add_x2 v[98:99], v[0:1], off
.LBB0_886:
	s_or_b64 exec, exec, s[22:23]
	s_waitcnt lgkmcnt(0)
	v_or_b32_e32 v98, 32, v146
	v_ashrrev_i32_e32 v99, 31, v98
	v_lshlrev_b64 v[100:101], 10, v[98:99]
	v_lshl_add_u64 v[100:101], v[100:101], 0, v[144:145]
	v_lshl_add_u64 v[104:105], v[100:101], 1, s[44:45]
	s_waitcnt vmcnt(17)
	v_lshlrev_b32_e32 v106, 16, v208
	v_and_b32_e32 v107, 0xffff0000, v208
	v_lshlrev_b32_e32 v100, 16, v209
	v_and_b32_e32 v101, 0xffff0000, v209
	v_lshlrev_b32_e32 v108, 16, v210
	v_and_b32_e32 v109, 0xffff0000, v210
	v_lshlrev_b32_e32 v102, 16, v211
	v_and_b32_e32 v103, 0xffff0000, v211
	v_pk_add_f32 v[96:97], v[96:97], v[100:101]
	v_pk_add_f32 v[94:95], v[94:95], v[106:107]
	v_pk_add_f32 v[100:101], v[92:93], v[102:103]
	v_pk_add_f32 v[102:103], v[90:91], v[108:109]
	v_cvt_pk_bf16_f32 v90, v94, v95
	v_cvt_pk_bf16_f32 v91, v96, v97
	v_cvt_pk_bf16_f32 v92, v102, v103
	v_cvt_pk_bf16_f32 v93, v100, v101
	global_store_dwordx4 v[104:105], v[90:93], off
	v_mul_f32_e32 v0, v95, v95
	v_fmac_f32_e32 v0, v94, v94
	v_mul_f32_e32 v90, v97, v97
	v_fmac_f32_e32 v90, v96, v96
	v_add_f32_e32 v0, v0, v90
	v_mul_f32_e32 v90, v103, v103
	v_fmac_f32_e32 v90, v102, v102
	v_add_f32_e32 v0, v90, v0
	v_mul_f32_e32 v90, v101, v101
	v_fmac_f32_e32 v90, v100, v100
	v_add_f32_e32 v0, v90, v0
	s_waitcnt vmcnt(17)
	v_lshlrev_b32_e32 v94, 16, v212
	v_and_b32_e32 v95, 0xffff0000, v212
	v_lshlrev_b32_e32 v90, 16, v213
	v_and_b32_e32 v91, 0xffff0000, v213
	v_lshlrev_b32_e32 v96, 16, v214
	v_and_b32_e32 v97, 0xffff0000, v214
	v_lshlrev_b32_e32 v92, 16, v215
	v_and_b32_e32 v93, 0xffff0000, v215
	v_pk_add_f32 v[88:89], v[88:89], v[90:91]
	v_pk_add_f32 v[86:87], v[86:87], v[94:95]
	v_pk_add_f32 v[90:91], v[84:85], v[92:93]
	v_pk_add_f32 v[92:93], v[82:83], v[96:97]
	v_cvt_pk_bf16_f32 v82, v86, v87
	v_cvt_pk_bf16_f32 v83, v88, v89
	v_cvt_pk_bf16_f32 v84, v92, v93
	v_cvt_pk_bf16_f32 v85, v90, v91
	global_store_dwordx4 v[104:105], v[82:85], off offset:256
	s_nop 1
	v_mul_f32_e32 v82, v87, v87
	v_mul_f32_e32 v83, v89, v89
	v_fmac_f32_e32 v82, v86, v86
	v_fmac_f32_e32 v83, v88, v88
	v_add_f32_e32 v82, v82, v83
	v_mul_f32_e32 v83, v93, v93
	v_fmac_f32_e32 v83, v92, v92
	v_add_f32_e32 v82, v83, v82
	v_mul_f32_e32 v83, v91, v91
	v_fmac_f32_e32 v83, v90, v90
	v_add_f32_e32 v82, v83, v82
	v_add_f32_e32 v0, v0, v82
	ds_bpermute_b32 v82, v153, v0
	s_waitcnt lgkmcnt(0)
	v_add_f32_e32 v0, v0, v82
	ds_bpermute_b32 v82, v152, v0
	s_and_saveexec_b64 s[22:23], s[2:3]
	s_cbranch_execz .LBB0_888
	s_waitcnt lgkmcnt(0)
	v_add_f32_e32 v0, v0, v82
	v_fma_f32 v0, v0, s82, 0.5
	v_cvt_u32_f32_e32 v0, v0
	v_lshl_add_u64 v[82:83], v[98:99], 3, s[80:81]
	global_atomic_add_x2 v[82:83], v[0:1], off
.LBB0_888:
	s_or_b64 exec, exec, s[22:23]
	s_waitcnt lgkmcnt(0)
	v_or_b32_e32 v82, 48, v146
	v_ashrrev_i32_e32 v83, 31, v82
	v_lshlrev_b64 v[84:85], 10, v[82:83]
	v_lshl_add_u64 v[84:85], v[84:85], 0, v[144:145]
	v_lshl_add_u64 v[88:89], v[84:85], 1, s[44:45]
	s_waitcnt vmcnt(18)
	v_lshlrev_b32_e32 v90, 16, v216
	v_and_b32_e32 v91, 0xffff0000, v216
	v_lshlrev_b32_e32 v84, 16, v217
	v_and_b32_e32 v85, 0xffff0000, v217
	v_lshlrev_b32_e32 v92, 16, v218
	v_and_b32_e32 v93, 0xffff0000, v218
	v_lshlrev_b32_e32 v86, 16, v219
	v_and_b32_e32 v87, 0xffff0000, v219
	v_pk_add_f32 v[80:81], v[80:81], v[84:85]
	v_pk_add_f32 v[78:79], v[78:79], v[90:91]
	v_pk_add_f32 v[84:85], v[76:77], v[86:87]
	v_pk_add_f32 v[86:87], v[74:75], v[92:93]
	v_cvt_pk_bf16_f32 v74, v78, v79
	v_cvt_pk_bf16_f32 v75, v80, v81
	v_cvt_pk_bf16_f32 v76, v86, v87
	v_cvt_pk_bf16_f32 v77, v84, v85
	global_store_dwordx4 v[88:89], v[74:77], off
	v_mul_f32_e32 v0, v79, v79
	v_fmac_f32_e32 v0, v78, v78
	v_mul_f32_e32 v74, v81, v81
	v_fmac_f32_e32 v74, v80, v80
	v_add_f32_e32 v0, v0, v74
	v_mul_f32_e32 v74, v87, v87
	v_fmac_f32_e32 v74, v86, v86
	v_add_f32_e32 v0, v74, v0
	v_mul_f32_e32 v74, v85, v85
	v_fmac_f32_e32 v74, v84, v84
	v_add_f32_e32 v0, v74, v0
	s_waitcnt vmcnt(18)
	v_lshlrev_b32_e32 v78, 16, v220
	v_and_b32_e32 v79, 0xffff0000, v220
	v_lshlrev_b32_e32 v74, 16, v221
	v_and_b32_e32 v75, 0xffff0000, v221
	v_lshlrev_b32_e32 v80, 16, v222
	v_and_b32_e32 v81, 0xffff0000, v222
	v_lshlrev_b32_e32 v76, 16, v223
	v_and_b32_e32 v77, 0xffff0000, v223
	v_pk_add_f32 v[72:73], v[72:73], v[74:75]
	v_pk_add_f32 v[70:71], v[70:71], v[78:79]
	v_pk_add_f32 v[74:75], v[68:69], v[76:77]
	v_pk_add_f32 v[76:77], v[66:67], v[80:81]
	v_cvt_pk_bf16_f32 v66, v70, v71
	v_cvt_pk_bf16_f32 v67, v72, v73
	v_cvt_pk_bf16_f32 v68, v76, v77
	v_cvt_pk_bf16_f32 v69, v74, v75
	global_store_dwordx4 v[88:89], v[66:69], off offset:256
	s_nop 1
	v_mul_f32_e32 v66, v71, v71
	v_mul_f32_e32 v67, v73, v73
	v_fmac_f32_e32 v66, v70, v70
	v_fmac_f32_e32 v67, v72, v72
	v_add_f32_e32 v66, v66, v67
	v_mul_f32_e32 v67, v77, v77
	v_fmac_f32_e32 v67, v76, v76
	v_add_f32_e32 v66, v67, v66
	v_mul_f32_e32 v67, v75, v75
	v_fmac_f32_e32 v67, v74, v74
	v_add_f32_e32 v66, v67, v66
	v_add_f32_e32 v0, v0, v66
	ds_bpermute_b32 v66, v153, v0
	s_waitcnt lgkmcnt(0)
	v_add_f32_e32 v0, v0, v66
	ds_bpermute_b32 v66, v152, v0
	s_and_saveexec_b64 s[22:23], s[2:3]
	s_cbranch_execz .LBB0_890
	s_waitcnt lgkmcnt(0)
	v_add_f32_e32 v0, v0, v66
	v_fma_f32 v0, v0, s82, 0.5
	v_cvt_u32_f32_e32 v0, v0
	v_lshl_add_u64 v[66:67], v[82:83], 3, s[80:81]
	global_atomic_add_x2 v[66:67], v[0:1], off
.LBB0_890:
	s_or_b64 exec, exec, s[22:23]
	s_waitcnt lgkmcnt(0)
	v_add_u32_e32 v66, 0x80, v146
	v_ashrrev_i32_e32 v67, 31, v66
	v_lshlrev_b64 v[68:69], 10, v[66:67]
	v_lshl_add_u64 v[68:69], v[68:69], 0, v[144:145]
	v_lshl_add_u64 v[72:73], v[68:69], 1, s[44:45]
	s_waitcnt vmcnt(19)
	v_lshlrev_b32_e32 v74, 16, v224
	v_and_b32_e32 v75, 0xffff0000, v224
	v_lshlrev_b32_e32 v68, 16, v225
	v_and_b32_e32 v69, 0xffff0000, v225
	v_lshlrev_b32_e32 v76, 16, v226
	v_and_b32_e32 v77, 0xffff0000, v226
	v_lshlrev_b32_e32 v70, 16, v227
	v_and_b32_e32 v71, 0xffff0000, v227
	v_pk_add_f32 v[64:65], v[64:65], v[68:69]
	v_pk_add_f32 v[62:63], v[62:63], v[74:75]
	v_pk_add_f32 v[68:69], v[60:61], v[70:71]
	v_pk_add_f32 v[70:71], v[58:59], v[76:77]
	v_cvt_pk_bf16_f32 v58, v62, v63
	v_cvt_pk_bf16_f32 v59, v64, v65
	v_cvt_pk_bf16_f32 v60, v70, v71
	v_cvt_pk_bf16_f32 v61, v68, v69
	global_store_dwordx4 v[72:73], v[58:61], off
	v_mul_f32_e32 v0, v63, v63
	v_fmac_f32_e32 v0, v62, v62
	v_mul_f32_e32 v58, v65, v65
	v_fmac_f32_e32 v58, v64, v64
	v_add_f32_e32 v0, v0, v58
	v_mul_f32_e32 v58, v71, v71
	v_fmac_f32_e32 v58, v70, v70
	v_add_f32_e32 v0, v58, v0
	v_mul_f32_e32 v58, v69, v69
	v_fmac_f32_e32 v58, v68, v68
	v_add_f32_e32 v0, v58, v0
	s_waitcnt vmcnt(19)
	v_lshlrev_b32_e32 v62, 16, v228
	v_and_b32_e32 v63, 0xffff0000, v228
	v_lshlrev_b32_e32 v58, 16, v229
	v_and_b32_e32 v59, 0xffff0000, v229
	v_lshlrev_b32_e32 v64, 16, v230
	v_and_b32_e32 v65, 0xffff0000, v230
	v_lshlrev_b32_e32 v60, 16, v231
	v_and_b32_e32 v61, 0xffff0000, v231
	v_pk_add_f32 v[56:57], v[56:57], v[58:59]
	v_pk_add_f32 v[54:55], v[54:55], v[62:63]
	v_pk_add_f32 v[58:59], v[52:53], v[60:61]
	v_pk_add_f32 v[60:61], v[50:51], v[64:65]
	v_cvt_pk_bf16_f32 v50, v54, v55
	v_cvt_pk_bf16_f32 v51, v56, v57
	v_cvt_pk_bf16_f32 v52, v60, v61
	v_cvt_pk_bf16_f32 v53, v58, v59
	global_store_dwordx4 v[72:73], v[50:53], off offset:256
	s_nop 1
	v_mul_f32_e32 v50, v55, v55
	v_mul_f32_e32 v51, v57, v57
	v_fmac_f32_e32 v50, v54, v54
	v_fmac_f32_e32 v51, v56, v56
	v_add_f32_e32 v50, v50, v51
	v_mul_f32_e32 v51, v61, v61
	v_fmac_f32_e32 v51, v60, v60
	v_add_f32_e32 v50, v51, v50
	v_mul_f32_e32 v51, v59, v59
	v_fmac_f32_e32 v51, v58, v58
	v_add_f32_e32 v50, v51, v50
	v_add_f32_e32 v0, v0, v50
	ds_bpermute_b32 v50, v153, v0
	s_waitcnt lgkmcnt(0)
	v_add_f32_e32 v0, v0, v50
	ds_bpermute_b32 v50, v152, v0
	s_and_saveexec_b64 s[22:23], s[2:3]
	s_cbranch_execz .LBB0_892
	s_waitcnt lgkmcnt(0)
	v_add_f32_e32 v0, v0, v50
	v_fma_f32 v0, v0, s82, 0.5
	v_cvt_u32_f32_e32 v0, v0
	v_lshl_add_u64 v[50:51], v[66:67], 3, s[80:81]
	global_atomic_add_x2 v[50:51], v[0:1], off
.LBB0_892:
	s_or_b64 exec, exec, s[22:23]
	s_waitcnt lgkmcnt(0)
	v_add_u32_e32 v50, 0x90, v146
	v_ashrrev_i32_e32 v51, 31, v50
	v_lshlrev_b64 v[52:53], 10, v[50:51]
	v_lshl_add_u64 v[52:53], v[52:53], 0, v[144:145]
	v_lshl_add_u64 v[56:57], v[52:53], 1, s[44:45]
	s_waitcnt vmcnt(20)
	v_lshlrev_b32_e32 v58, 16, v232
	v_and_b32_e32 v59, 0xffff0000, v232
	v_lshlrev_b32_e32 v52, 16, v233
	v_and_b32_e32 v53, 0xffff0000, v233
	v_lshlrev_b32_e32 v60, 16, v234
	v_and_b32_e32 v61, 0xffff0000, v234
	v_lshlrev_b32_e32 v54, 16, v235
	v_and_b32_e32 v55, 0xffff0000, v235
	v_pk_add_f32 v[48:49], v[48:49], v[52:53]
	v_pk_add_f32 v[46:47], v[46:47], v[58:59]
	v_pk_add_f32 v[52:53], v[44:45], v[54:55]
	v_pk_add_f32 v[54:55], v[42:43], v[60:61]
	v_cvt_pk_bf16_f32 v42, v46, v47
	v_cvt_pk_bf16_f32 v43, v48, v49
	v_cvt_pk_bf16_f32 v44, v54, v55
	v_cvt_pk_bf16_f32 v45, v52, v53
	global_store_dwordx4 v[56:57], v[42:45], off
	v_mul_f32_e32 v0, v47, v47
	v_fmac_f32_e32 v0, v46, v46
	v_mul_f32_e32 v42, v49, v49
	v_fmac_f32_e32 v42, v48, v48
	v_add_f32_e32 v0, v0, v42
	v_mul_f32_e32 v42, v55, v55
	v_fmac_f32_e32 v42, v54, v54
	v_add_f32_e32 v0, v42, v0
	v_mul_f32_e32 v42, v53, v53
	v_fmac_f32_e32 v42, v52, v52
	v_add_f32_e32 v0, v42, v0
	s_waitcnt vmcnt(20)
	v_lshlrev_b32_e32 v46, 16, v236
	v_and_b32_e32 v47, 0xffff0000, v236
	v_lshlrev_b32_e32 v42, 16, v237
	v_and_b32_e32 v43, 0xffff0000, v237
	v_lshlrev_b32_e32 v48, 16, v238
	v_and_b32_e32 v49, 0xffff0000, v238
	v_lshlrev_b32_e32 v44, 16, v239
	v_and_b32_e32 v45, 0xffff0000, v239
	v_pk_add_f32 v[40:41], v[40:41], v[42:43]
	v_pk_add_f32 v[38:39], v[38:39], v[46:47]
	v_pk_add_f32 v[42:43], v[36:37], v[44:45]
	v_pk_add_f32 v[44:45], v[34:35], v[48:49]
	v_cvt_pk_bf16_f32 v34, v38, v39
	v_cvt_pk_bf16_f32 v35, v40, v41
	v_cvt_pk_bf16_f32 v36, v44, v45
	v_cvt_pk_bf16_f32 v37, v42, v43
	global_store_dwordx4 v[56:57], v[34:37], off offset:256
	s_nop 1
	v_mul_f32_e32 v34, v39, v39
	v_mul_f32_e32 v35, v41, v41
	v_fmac_f32_e32 v34, v38, v38
	v_fmac_f32_e32 v35, v40, v40
	v_add_f32_e32 v34, v34, v35
	v_mul_f32_e32 v35, v45, v45
	v_fmac_f32_e32 v35, v44, v44
	v_add_f32_e32 v34, v35, v34
	v_mul_f32_e32 v35, v43, v43
	v_fmac_f32_e32 v35, v42, v42
	v_add_f32_e32 v34, v35, v34
	v_add_f32_e32 v0, v0, v34
	ds_bpermute_b32 v34, v153, v0
	s_waitcnt lgkmcnt(0)
	v_add_f32_e32 v0, v0, v34
	ds_bpermute_b32 v34, v152, v0
	s_and_saveexec_b64 s[22:23], s[2:3]
	s_cbranch_execz .LBB0_894
	s_waitcnt lgkmcnt(0)
	v_add_f32_e32 v0, v0, v34
	v_fma_f32 v0, v0, s82, 0.5
	v_cvt_u32_f32_e32 v0, v0
	v_lshl_add_u64 v[34:35], v[50:51], 3, s[80:81]
	global_atomic_add_x2 v[34:35], v[0:1], off
.LBB0_894:
	s_or_b64 exec, exec, s[22:23]
	s_waitcnt lgkmcnt(0)
	v_add_u32_e32 v34, 0xa0, v146
	v_ashrrev_i32_e32 v35, 31, v34
	v_lshlrev_b64 v[36:37], 10, v[34:35]
	v_lshl_add_u64 v[36:37], v[36:37], 0, v[144:145]
	v_lshl_add_u64 v[40:41], v[36:37], 1, s[44:45]
	s_waitcnt vmcnt(21)
	v_lshlrev_b32_e32 v42, 16, v240
	v_and_b32_e32 v43, 0xffff0000, v240
	v_lshlrev_b32_e32 v36, 16, v241
	v_and_b32_e32 v37, 0xffff0000, v241
	v_lshlrev_b32_e32 v44, 16, v242
	v_and_b32_e32 v45, 0xffff0000, v242
	v_lshlrev_b32_e32 v38, 16, v243
	v_and_b32_e32 v39, 0xffff0000, v243
	v_pk_add_f32 v[32:33], v[32:33], v[36:37]
	v_pk_add_f32 v[30:31], v[30:31], v[42:43]
	v_pk_add_f32 v[36:37], v[28:29], v[38:39]
	v_pk_add_f32 v[38:39], v[26:27], v[44:45]
	v_cvt_pk_bf16_f32 v26, v30, v31
	v_cvt_pk_bf16_f32 v27, v32, v33
	v_cvt_pk_bf16_f32 v28, v38, v39
	v_cvt_pk_bf16_f32 v29, v36, v37
	global_store_dwordx4 v[40:41], v[26:29], off
	v_mul_f32_e32 v0, v31, v31
	v_fmac_f32_e32 v0, v30, v30
	v_mul_f32_e32 v26, v33, v33
	v_fmac_f32_e32 v26, v32, v32
	v_add_f32_e32 v0, v0, v26
	v_mul_f32_e32 v26, v39, v39
	v_fmac_f32_e32 v26, v38, v38
	v_add_f32_e32 v0, v26, v0
	v_mul_f32_e32 v26, v37, v37
	v_fmac_f32_e32 v26, v36, v36
	v_add_f32_e32 v0, v26, v0
	s_waitcnt vmcnt(21)
	v_lshlrev_b32_e32 v30, 16, v244
	v_and_b32_e32 v31, 0xffff0000, v244
	v_lshlrev_b32_e32 v26, 16, v245
	v_and_b32_e32 v27, 0xffff0000, v245
	v_lshlrev_b32_e32 v32, 16, v246
	v_and_b32_e32 v33, 0xffff0000, v246
	v_lshlrev_b32_e32 v28, 16, v247
	v_and_b32_e32 v29, 0xffff0000, v247
	v_pk_add_f32 v[24:25], v[24:25], v[26:27]
	v_pk_add_f32 v[22:23], v[22:23], v[30:31]
	v_pk_add_f32 v[26:27], v[20:21], v[28:29]
	v_pk_add_f32 v[28:29], v[18:19], v[32:33]
	v_cvt_pk_bf16_f32 v18, v22, v23
	v_cvt_pk_bf16_f32 v19, v24, v25
	v_cvt_pk_bf16_f32 v20, v28, v29
	v_cvt_pk_bf16_f32 v21, v26, v27
	global_store_dwordx4 v[40:41], v[18:21], off offset:256
	s_nop 1
	v_mul_f32_e32 v18, v23, v23
	v_mul_f32_e32 v19, v25, v25
	v_fmac_f32_e32 v18, v22, v22
	v_fmac_f32_e32 v19, v24, v24
	v_add_f32_e32 v18, v18, v19
	v_mul_f32_e32 v19, v29, v29
	v_fmac_f32_e32 v19, v28, v28
	v_add_f32_e32 v18, v19, v18
	v_mul_f32_e32 v19, v27, v27
	v_fmac_f32_e32 v19, v26, v26
	v_add_f32_e32 v18, v19, v18
	v_add_f32_e32 v0, v0, v18
	ds_bpermute_b32 v18, v153, v0
	s_waitcnt lgkmcnt(0)
	v_add_f32_e32 v0, v0, v18
	ds_bpermute_b32 v18, v152, v0
	s_and_saveexec_b64 s[22:23], s[2:3]
	s_cbranch_execz .LBB0_896
	s_waitcnt lgkmcnt(0)
	v_add_f32_e32 v0, v0, v18
	v_fma_f32 v0, v0, s82, 0.5
	v_cvt_u32_f32_e32 v0, v0
	v_lshl_add_u64 v[18:19], v[34:35], 3, s[80:81]
	global_atomic_add_x2 v[18:19], v[0:1], off
.LBB0_896:
	s_or_b64 exec, exec, s[22:23]
	s_waitcnt lgkmcnt(0)
	v_add_u32_e32 v18, 0xb0, v146
	v_ashrrev_i32_e32 v19, 31, v18
	v_lshlrev_b64 v[20:21], 10, v[18:19]
	v_lshl_add_u64 v[20:21], v[20:21], 0, v[144:145]
	v_lshl_add_u64 v[24:25], v[20:21], 1, s[44:45]
	s_waitcnt vmcnt(19)
	v_lshlrev_b32_e32 v26, 16, v186
	v_and_b32_e32 v27, 0xffff0000, v186
	v_lshlrev_b32_e32 v20, 16, v187
	v_and_b32_e32 v21, 0xffff0000, v187
	v_lshlrev_b32_e32 v28, 16, v188
	v_and_b32_e32 v29, 0xffff0000, v188
	v_lshlrev_b32_e32 v22, 16, v189
	v_and_b32_e32 v23, 0xffff0000, v189
	v_pk_add_f32 v[16:17], v[16:17], v[20:21]
	v_pk_add_f32 v[14:15], v[14:15], v[26:27]
	v_pk_add_f32 v[20:21], v[12:13], v[22:23]
	v_pk_add_f32 v[22:23], v[10:11], v[28:29]
	v_cvt_pk_bf16_f32 v10, v14, v15
	v_cvt_pk_bf16_f32 v11, v16, v17
	v_cvt_pk_bf16_f32 v12, v22, v23
	v_cvt_pk_bf16_f32 v13, v20, v21
	global_store_dwordx4 v[24:25], v[10:13], off
	v_mul_f32_e32 v0, v15, v15
	v_fmac_f32_e32 v0, v14, v14
	v_mul_f32_e32 v10, v17, v17
	v_fmac_f32_e32 v10, v16, v16
	v_add_f32_e32 v0, v0, v10
	v_mul_f32_e32 v10, v23, v23
	v_fmac_f32_e32 v10, v22, v22
	v_add_f32_e32 v0, v10, v0
	v_mul_f32_e32 v10, v21, v21
	v_fmac_f32_e32 v10, v20, v20
	v_add_f32_e32 v0, v10, v0
	s_waitcnt vmcnt(19)
	v_lshlrev_b32_e32 v14, 16, v190
	v_and_b32_e32 v15, 0xffff0000, v190
	v_lshlrev_b32_e32 v10, 16, v191
	v_and_b32_e32 v11, 0xffff0000, v191
	v_lshlrev_b32_e32 v16, 16, v192
	v_and_b32_e32 v17, 0xffff0000, v192
	v_lshlrev_b32_e32 v12, 16, v193
	v_and_b32_e32 v13, 0xffff0000, v193
	v_pk_add_f32 v[8:9], v[8:9], v[10:11]
	v_pk_add_f32 v[6:7], v[6:7], v[14:15]
	v_pk_add_f32 v[10:11], v[4:5], v[12:13]
	v_pk_add_f32 v[12:13], v[2:3], v[16:17]
	v_cvt_pk_bf16_f32 v2, v6, v7
	v_cvt_pk_bf16_f32 v3, v8, v9
	v_cvt_pk_bf16_f32 v4, v12, v13
	v_cvt_pk_bf16_f32 v5, v10, v11
	global_store_dwordx4 v[24:25], v[2:5], off offset:256
	s_nop 1
	v_mul_f32_e32 v2, v7, v7
	v_mul_f32_e32 v3, v9, v9
	v_fmac_f32_e32 v2, v6, v6
	v_fmac_f32_e32 v3, v8, v8
	v_add_f32_e32 v2, v2, v3
	v_mul_f32_e32 v3, v13, v13
	v_fmac_f32_e32 v3, v12, v12
	v_add_f32_e32 v2, v3, v2
	v_mul_f32_e32 v3, v11, v11
	v_fmac_f32_e32 v3, v10, v10
	v_add_f32_e32 v2, v3, v2
	v_add_f32_e32 v0, v0, v2
	ds_bpermute_b32 v2, v153, v0
	s_waitcnt lgkmcnt(0)
	v_add_f32_e32 v0, v0, v2
	ds_bpermute_b32 v2, v152, v0
	s_and_saveexec_b64 s[22:23], s[2:3]
	s_cbranch_execz .LBB0_898
	s_waitcnt lgkmcnt(0)
	v_add_f32_e32 v0, v0, v2
	v_fma_f32 v0, v0, s82, 0.5
	v_cvt_u32_f32_e32 v0, v0
	v_lshl_add_u64 v[4:5], v[18:19], 3, s[80:81]
	global_atomic_add_x2 v[4:5], v[0:1], off

.LBB0_1032:
	v_and_b32_e32 v147, 64, v199
	v_xor_b32_e32 v0, 16, v199
	v_add_u32_e32 v147, 64, v147
	v_cmp_lt_i32_e32 vcc, v0, v147
	v_lshl_add_u32 v146, s14, 8, v139
	s_lshl_b32 s12, s33, 8
	v_cndmask_b32_e32 v0, v199, v0, vcc
	v_lshlrev_b32_e32 v153, 2, v0
	v_xor_b32_e32 v0, 32, v199
	s_ashr_i32 s13, s12, 31
	v_cmp_lt_i32_e32 vcc, v0, v147
	v_ashrrev_i32_e32 v147, 31, v146
	v_mov_b32_e32 v145, s13
	v_or_b32_e32 v144, s12, v138
	v_lshlrev_b64 v[148:149], 10, v[146:147]
	v_lshl_add_u64 v[148:149], v[148:149], 0, v[144:145]
	v_lshl_add_u64 v[148:149], v[148:149], 1, s[44:45]
	v_lshl_add_u32 v250, v146, 10, v144
	v_lshlrev_b32_e32 v250, 1, v250
	s_add_u32 s98, s44, 0x0
	s_addc_u32 s99, s45, 0
	global_load_dwordx4 v[186:189], v250, s[98:99]
	global_load_dwordx4 v[190:193], v250, s[98:99] offset:256
	s_add_u32 s100, s44, 0x8000
	s_addc_u32 s101, s45, 0
	global_load_dwordx4 v[200:203], v250, s[100:101]
	global_load_dwordx4 v[204:207], v250, s[100:101] offset:256
	s_add_u32 s98, s44, 0x10000
	s_addc_u32 s99, s45, 0
	global_load_dwordx4 v[208:211], v250, s[98:99]
	global_load_dwordx4 v[212:215], v250, s[98:99] offset:256
	s_add_u32 s100, s44, 0x18000
	s_addc_u32 s101, s45, 0
	global_load_dwordx4 v[216:219], v250, s[100:101]
	global_load_dwordx4 v[220:223], v250, s[100:101] offset:256
	s_add_u32 s98, s44, 0x40000
	s_addc_u32 s99, s45, 0
	global_load_dwordx4 v[224:227], v250, s[98:99]
	global_load_dwordx4 v[228:231], v250, s[98:99] offset:256
	s_add_u32 s100, s44, 0x48000
	s_addc_u32 s101, s45, 0
	global_load_dwordx4 v[232:235], v250, s[100:101]
	global_load_dwordx4 v[236:239], v250, s[100:101] offset:256
	s_add_u32 s98, s44, 0x50000
	s_addc_u32 s99, s45, 0
	global_load_dwordx4 v[240:243], v250, s[98:99]
	global_load_dwordx4 v[244:247], v250, s[98:99] offset:256
	v_cndmask_b32_e32 v0, v199, v0, vcc
	v_lshlrev_b32_e32 v152, 2, v0
	s_waitcnt vmcnt(13)
	v_lshlrev_b32_e32 v182, 16, v186
	v_and_b32_e32 v183, 0xffff0000, v186
	v_lshlrev_b32_e32 v154, 16, v187
	v_and_b32_e32 v155, 0xffff0000, v187
	v_lshlrev_b32_e32 v184, 16, v188
	v_and_b32_e32 v185, 0xffff0000, v188
	v_lshlrev_b32_e32 v156, 16, v189
	v_and_b32_e32 v157, 0xffff0000, v189
	v_pk_add_f32 v[128:129], v[128:129], v[154:155]
	v_pk_add_f32 v[126:127], v[126:127], v[182:183]
	v_pk_add_f32 v[154:155], v[124:125], v[156:157]
	v_pk_add_f32 v[156:157], v[122:123], v[184:185]
	v_cvt_pk_bf16_f32 v122, v126, v127
	v_cvt_pk_bf16_f32 v123, v128, v129
	v_cvt_pk_bf16_f32 v124, v156, v157
	v_cvt_pk_bf16_f32 v125, v154, v155
	global_store_dwordx4 v[148:149], v[122:125], off
	v_mul_f32_e32 v0, v127, v127
	v_fmac_f32_e32 v0, v126, v126
	v_mul_f32_e32 v122, v129, v129
	v_fmac_f32_e32 v122, v128, v128
	v_add_f32_e32 v0, v0, v122
	v_mul_f32_e32 v122, v157, v157
	v_fmac_f32_e32 v122, v156, v156
	v_add_f32_e32 v0, v122, v0
	v_mul_f32_e32 v122, v155, v155
	v_fmac_f32_e32 v122, v154, v154
	v_add_f32_e32 v0, v122, v0
	s_waitcnt vmcnt(13)
	v_lshlrev_b32_e32 v126, 16, v190
	v_and_b32_e32 v127, 0xffff0000, v190
	v_lshlrev_b32_e32 v122, 16, v191
	v_and_b32_e32 v123, 0xffff0000, v191
	v_lshlrev_b32_e32 v128, 16, v192
	v_and_b32_e32 v129, 0xffff0000, v192
	v_lshlrev_b32_e32 v124, 16, v193
	v_and_b32_e32 v125, 0xffff0000, v193
	v_pk_add_f32 v[120:121], v[120:121], v[122:123]
	v_pk_add_f32 v[118:119], v[118:119], v[126:127]
	v_pk_add_f32 v[122:123], v[116:117], v[124:125]
	v_pk_add_f32 v[124:125], v[114:115], v[128:129]
	v_cvt_pk_bf16_f32 v114, v118, v119
	v_cvt_pk_bf16_f32 v115, v120, v121
	v_cvt_pk_bf16_f32 v116, v124, v125
	v_cvt_pk_bf16_f32 v117, v122, v123
	global_store_dwordx4 v[148:149], v[114:117], off offset:256
	s_nop 1
	v_mul_f32_e32 v114, v119, v119
	v_mul_f32_e32 v115, v121, v121
	v_fmac_f32_e32 v114, v118, v118
	v_fmac_f32_e32 v115, v120, v120
	v_add_f32_e32 v114, v114, v115
	v_mul_f32_e32 v115, v125, v125
	v_fmac_f32_e32 v115, v124, v124
	v_add_f32_e32 v114, v115, v114
	v_mul_f32_e32 v115, v123, v123
	v_fmac_f32_e32 v115, v122, v122
	v_add_f32_e32 v114, v115, v114
	v_add_f32_e32 v0, v0, v114
	ds_bpermute_b32 v114, v153, v0
	s_waitcnt lgkmcnt(0)
	v_add_f32_e32 v0, v0, v114
	ds_bpermute_b32 v114, v152, v0
	s_and_saveexec_b64 s[22:23], s[2:3]
	s_cbranch_execz .LBB0_1034
	s_waitcnt lgkmcnt(0)
	v_add_f32_e32 v0, v0, v114
	v_fma_f32 v0, v0, s82, 0.5
	v_cvt_u32_f32_e32 v0, v0
	v_lshl_add_u64 v[114:115], v[146:147], 3, s[16:17]
	global_atomic_add_x2 v[114:115], v[0:1], off
.LBB0_1034:
	s_or_b64 exec, exec, s[22:23]
	s_add_u32 s100, s44, 0x58000
	s_addc_u32 s101, s45, 0
	global_load_dwordx4 v[186:189], v250, s[100:101]
	global_load_dwordx4 v[190:193], v250, s[100:101] offset:256
	s_waitcnt lgkmcnt(0)
	v_or_b32_e32 v114, 16, v146
	v_ashrrev_i32_e32 v115, 31, v114
	v_lshlrev_b64 v[116:117], 10, v[114:115]
	v_lshl_add_u64 v[116:117], v[116:117], 0, v[144:145]
	v_lshl_add_u64 v[120:121], v[116:117], 1, s[44:45]
	s_waitcnt vmcnt(16)
	v_lshlrev_b32_e32 v122, 16, v200
	v_and_b32_e32 v123, 0xffff0000, v200
	v_lshlrev_b32_e32 v116, 16, v201
	v_and_b32_e32 v117, 0xffff0000, v201
	v_lshlrev_b32_e32 v124, 16, v202
	v_and_b32_e32 v125, 0xffff0000, v202
	v_lshlrev_b32_e32 v118, 16, v203
	v_and_b32_e32 v119, 0xffff0000, v203
	v_pk_add_f32 v[112:113], v[112:113], v[116:117]
	v_pk_add_f32 v[110:111], v[110:111], v[122:123]
	v_pk_add_f32 v[116:117], v[108:109], v[118:119]
	v_pk_add_f32 v[118:119], v[106:107], v[124:125]
	v_cvt_pk_bf16_f32 v106, v110, v111
	v_cvt_pk_bf16_f32 v107, v112, v113
	v_cvt_pk_bf16_f32 v108, v118, v119
	v_cvt_pk_bf16_f32 v109, v116, v117
	global_store_dwordx4 v[120:121], v[106:109], off
	v_mul_f32_e32 v0, v111, v111
	v_fmac_f32_e32 v0, v110, v110
	v_mul_f32_e32 v106, v113, v113
	v_fmac_f32_e32 v106, v112, v112
	v_add_f32_e32 v0, v0, v106
	v_mul_f32_e32 v106, v119, v119
	v_fmac_f32_e32 v106, v118, v118
	v_add_f32_e32 v0, v106, v0
	v_mul_f32_e32 v106, v117, v117
	v_fmac_f32_e32 v106, v116, v116
	v_add_f32_e32 v0, v106, v0
	s_waitcnt vmcnt(16)
	v_lshlrev_b32_e32 v110, 16, v204
	v_and_b32_e32 v111, 0xffff0000, v204
	v_lshlrev_b32_e32 v106, 16, v205
	v_and_b32_e32 v107, 0xffff0000, v205
	v_lshlrev_b32_e32 v112, 16, v206
	v_and_b32_e32 v113, 0xffff0000, v206
	v_lshlrev_b32_e32 v108, 16, v207
	v_and_b32_e32 v109, 0xffff0000, v207
	v_pk_add_f32 v[104:105], v[104:105], v[106:107]
	v_pk_add_f32 v[102:103], v[102:103], v[110:111]
	v_pk_add_f32 v[106:107], v[100:101], v[108:109]
	v_pk_add_f32 v[108:109], v[98:99], v[112:113]
	v_cvt_pk_bf16_f32 v98, v102, v103
	v_cvt_pk_bf16_f32 v99, v104, v105
	v_cvt_pk_bf16_f32 v100, v108, v109
	v_cvt_pk_bf16_f32 v101, v106, v107
	global_store_dwordx4 v[120:121], v[98:101], off offset:256
	s_nop 1
	v_mul_f32_e32 v98, v103, v103
	v_mul_f32_e32 v99, v105, v105
	v_fmac_f32_e32 v98, v102, v102
	v_fmac_f32_e32 v99, v104, v104
	v_add_f32_e32 v98, v98, v99
	v_mul_f32_e32 v99, v109, v109
	v_fmac_f32_e32 v99, v108, v108
	v_add_f32_e32 v98, v99, v98
	v_mul_f32_e32 v99, v107, v107
	v_fmac_f32_e32 v99, v106, v106
	v_add_f32_e32 v98, v99, v98
	v_add_f32_e32 v0, v0, v98
	ds_bpermute_b32 v98, v153, v0
	s_waitcnt lgkmcnt(0)
	v_add_f32_e32 v0, v0, v98
	ds_bpermute_b32 v98, v152, v0
	s_and_saveexec_b64 s[22:23], s[2:3]
	s_cbranch_execz .LBB0_1036
	s_waitcnt lgkmcnt(0)
	v_add_f32_e32 v0, v0, v98
	v_fma_f32 v0, v0, s82, 0.5
	v_cvt_u32_f32_e32 v0, v0
	v_lshl_add_u64 v[98:99], v[114:115], 3, s[16:17]
	global_atomic_add_x2 v[98:99], v[0:1], off
.LBB0_1036:
	s_or_b64 exec, exec, s[22:23]
	s_waitcnt lgkmcnt(0)
	v_or_b32_e32 v98, 32, v146
	v_ashrrev_i32_e32 v99, 31, v98
	v_lshlrev_b64 v[100:101], 10, v[98:99]
	v_lshl_add_u64 v[100:101], v[100:101], 0, v[144:145]
	v_lshl_add_u64 v[104:105], v[100:101], 1, s[44:45]
	s_waitcnt vmcnt(17)
	v_lshlrev_b32_e32 v106, 16, v208
	v_and_b32_e32 v107, 0xffff0000, v208
	v_lshlrev_b32_e32 v100, 16, v209
	v_and_b32_e32 v101, 0xffff0000, v209
	v_lshlrev_b32_e32 v108, 16, v210
	v_and_b32_e32 v109, 0xffff0000, v210
	v_lshlrev_b32_e32 v102, 16, v211
	v_and_b32_e32 v103, 0xffff0000, v211
	v_pk_add_f32 v[96:97], v[96:97], v[100:101]
	v_pk_add_f32 v[94:95], v[94:95], v[106:107]
	v_pk_add_f32 v[100:101], v[92:93], v[102:103]
	v_pk_add_f32 v[102:103], v[90:91], v[108:109]
	v_cvt_pk_bf16_f32 v90, v94, v95
	v_cvt_pk_bf16_f32 v91, v96, v97
	v_cvt_pk_bf16_f32 v92, v102, v103
	v_cvt_pk_bf16_f32 v93, v100, v101
	global_store_dwordx4 v[104:105], v[90:93], off
	v_mul_f32_e32 v0, v95, v95
	v_fmac_f32_e32 v0, v94, v94
	v_mul_f32_e32 v90, v97, v97
	v_fmac_f32_e32 v90, v96, v96
	v_add_f32_e32 v0, v0, v90
	v_mul_f32_e32 v90, v103, v103
	v_fmac_f32_e32 v90, v102, v102
	v_add_f32_e32 v0, v90, v0
	v_mul_f32_e32 v90, v101, v101
	v_fmac_f32_e32 v90, v100, v100
	v_add_f32_e32 v0, v90, v0
	s_waitcnt vmcnt(17)
	v_lshlrev_b32_e32 v94, 16, v212
	v_and_b32_e32 v95, 0xffff0000, v212
	v_lshlrev_b32_e32 v90, 16, v213
	v_and_b32_e32 v91, 0xffff0000, v213
	v_lshlrev_b32_e32 v96, 16, v214
	v_and_b32_e32 v97, 0xffff0000, v214
	v_lshlrev_b32_e32 v92, 16, v215
	v_and_b32_e32 v93, 0xffff0000, v215
	v_pk_add_f32 v[88:89], v[88:89], v[90:91]
	v_pk_add_f32 v[86:87], v[86:87], v[94:95]
	v_pk_add_f32 v[90:91], v[84:85], v[92:93]
	v_pk_add_f32 v[92:93], v[82:83], v[96:97]
	v_cvt_pk_bf16_f32 v82, v86, v87
	v_cvt_pk_bf16_f32 v83, v88, v89
	v_cvt_pk_bf16_f32 v84, v92, v93
	v_cvt_pk_bf16_f32 v85, v90, v91
	global_store_dwordx4 v[104:105], v[82:85], off offset:256
	s_nop 1
	v_mul_f32_e32 v82, v87, v87
	v_mul_f32_e32 v83, v89, v89
	v_fmac_f32_e32 v82, v86, v86
	v_fmac_f32_e32 v83, v88, v88
	v_add_f32_e32 v82, v82, v83
	v_mul_f32_e32 v83, v93, v93
	v_fmac_f32_e32 v83, v92, v92
	v_add_f32_e32 v82, v83, v82
	v_mul_f32_e32 v83, v91, v91
	v_fmac_f32_e32 v83, v90, v90
	v_add_f32_e32 v82, v83, v82
	v_add_f32_e32 v0, v0, v82
	ds_bpermute_b32 v82, v153, v0
	s_waitcnt lgkmcnt(0)
	v_add_f32_e32 v0, v0, v82
	ds_bpermute_b32 v82, v152, v0
	s_and_saveexec_b64 s[22:23], s[2:3]
	s_cbranch_execz .LBB0_1038
	s_waitcnt lgkmcnt(0)
	v_add_f32_e32 v0, v0, v82
	v_fma_f32 v0, v0, s82, 0.5
	v_cvt_u32_f32_e32 v0, v0
	v_lshl_add_u64 v[82:83], v[98:99], 3, s[16:17]
	global_atomic_add_x2 v[82:83], v[0:1], off
.LBB0_1038:
	s_or_b64 exec, exec, s[22:23]
	s_waitcnt lgkmcnt(0)
	v_or_b32_e32 v82, 48, v146
	v_ashrrev_i32_e32 v83, 31, v82
	v_lshlrev_b64 v[84:85], 10, v[82:83]
	v_lshl_add_u64 v[84:85], v[84:85], 0, v[144:145]
	v_lshl_add_u64 v[88:89], v[84:85], 1, s[44:45]
	s_waitcnt vmcnt(18)
	v_lshlrev_b32_e32 v90, 16, v216
	v_and_b32_e32 v91, 0xffff0000, v216
	v_lshlrev_b32_e32 v84, 16, v217
	v_and_b32_e32 v85, 0xffff0000, v217
	v_lshlrev_b32_e32 v92, 16, v218
	v_and_b32_e32 v93, 0xffff0000, v218
	v_lshlrev_b32_e32 v86, 16, v219
	v_and_b32_e32 v87, 0xffff0000, v219
	v_pk_add_f32 v[80:81], v[80:81], v[84:85]
	v_pk_add_f32 v[78:79], v[78:79], v[90:91]
	v_pk_add_f32 v[84:85], v[76:77], v[86:87]
	v_pk_add_f32 v[86:87], v[74:75], v[92:93]
	v_cvt_pk_bf16_f32 v74, v78, v79
	v_cvt_pk_bf16_f32 v75, v80, v81
	v_cvt_pk_bf16_f32 v76, v86, v87
	v_cvt_pk_bf16_f32 v77, v84, v85
	global_store_dwordx4 v[88:89], v[74:77], off
	v_mul_f32_e32 v0, v79, v79
	v_fmac_f32_e32 v0, v78, v78
	v_mul_f32_e32 v74, v81, v81
	v_fmac_f32_e32 v74, v80, v80
	v_add_f32_e32 v0, v0, v74
	v_mul_f32_e32 v74, v87, v87
	v_fmac_f32_e32 v74, v86, v86
	v_add_f32_e32 v0, v74, v0
	v_mul_f32_e32 v74, v85, v85
	v_fmac_f32_e32 v74, v84, v84
	v_add_f32_e32 v0, v74, v0
	s_waitcnt vmcnt(18)
	v_lshlrev_b32_e32 v78, 16, v220
	v_and_b32_e32 v79, 0xffff0000, v220
	v_lshlrev_b32_e32 v74, 16, v221
	v_and_b32_e32 v75, 0xffff0000, v221
	v_lshlrev_b32_e32 v80, 16, v222
	v_and_b32_e32 v81, 0xffff0000, v222
	v_lshlrev_b32_e32 v76, 16, v223
	v_and_b32_e32 v77, 0xffff0000, v223
	v_pk_add_f32 v[72:73], v[72:73], v[74:75]
	v_pk_add_f32 v[70:71], v[70:71], v[78:79]
	v_pk_add_f32 v[74:75], v[68:69], v[76:77]
	v_pk_add_f32 v[76:77], v[66:67], v[80:81]
	v_cvt_pk_bf16_f32 v66, v70, v71
	v_cvt_pk_bf16_f32 v67, v72, v73
	v_cvt_pk_bf16_f32 v68, v76, v77
	v_cvt_pk_bf16_f32 v69, v74, v75
	global_store_dwordx4 v[88:89], v[66:69], off offset:256
	s_nop 1
	v_mul_f32_e32 v66, v71, v71
	v_mul_f32_e32 v67, v73, v73
	v_fmac_f32_e32 v66, v70, v70
	v_fmac_f32_e32 v67, v72, v72
	v_add_f32_e32 v66, v66, v67
	v_mul_f32_e32 v67, v77, v77
	v_fmac_f32_e32 v67, v76, v76
	v_add_f32_e32 v66, v67, v66
	v_mul_f32_e32 v67, v75, v75
	v_fmac_f32_e32 v67, v74, v74
	v_add_f32_e32 v66, v67, v66
	v_add_f32_e32 v0, v0, v66
	ds_bpermute_b32 v66, v153, v0
	s_waitcnt lgkmcnt(0)
	v_add_f32_e32 v0, v0, v66
	ds_bpermute_b32 v66, v152, v0
	s_and_saveexec_b64 s[22:23], s[2:3]
	s_cbranch_execz .LBB0_1040
	s_waitcnt lgkmcnt(0)
	v_add_f32_e32 v0, v0, v66
	v_fma_f32 v0, v0, s82, 0.5
	v_cvt_u32_f32_e32 v0, v0
	v_lshl_add_u64 v[66:67], v[82:83], 3, s[16:17]
	global_atomic_add_x2 v[66:67], v[0:1], off
.LBB0_1040:
	s_or_b64 exec, exec, s[22:23]
	s_waitcnt lgkmcnt(0)
	v_add_u32_e32 v66, 0x80, v146
	v_ashrrev_i32_e32 v67, 31, v66
	v_lshlrev_b64 v[68:69], 10, v[66:67]
	v_lshl_add_u64 v[68:69], v[68:69], 0, v[144:145]
	v_lshl_add_u64 v[72:73], v[68:69], 1, s[44:45]
	s_waitcnt vmcnt(19)
	v_lshlrev_b32_e32 v74, 16, v224
	v_and_b32_e32 v75, 0xffff0000, v224
	v_lshlrev_b32_e32 v68, 16, v225
	v_and_b32_e32 v69, 0xffff0000, v225
	v_lshlrev_b32_e32 v76, 16, v226
	v_and_b32_e32 v77, 0xffff0000, v226
	v_lshlrev_b32_e32 v70, 16, v227
	v_and_b32_e32 v71, 0xffff0000, v227
	v_pk_add_f32 v[64:65], v[64:65], v[68:69]
	v_pk_add_f32 v[62:63], v[62:63], v[74:75]
	v_pk_add_f32 v[68:69], v[60:61], v[70:71]
	v_pk_add_f32 v[70:71], v[58:59], v[76:77]
	v_cvt_pk_bf16_f32 v58, v62, v63
	v_cvt_pk_bf16_f32 v59, v64, v65
	v_cvt_pk_bf16_f32 v60, v70, v71
	v_cvt_pk_bf16_f32 v61, v68, v69
	global_store_dwordx4 v[72:73], v[58:61], off
	v_mul_f32_e32 v0, v63, v63
	v_fmac_f32_e32 v0, v62, v62
	v_mul_f32_e32 v58, v65, v65
	v_fmac_f32_e32 v58, v64, v64
	v_add_f32_e32 v0, v0, v58
	v_mul_f32_e32 v58, v71, v71
	v_fmac_f32_e32 v58, v70, v70
	v_add_f32_e32 v0, v58, v0
	v_mul_f32_e32 v58, v69, v69
	v_fmac_f32_e32 v58, v68, v68
	v_add_f32_e32 v0, v58, v0
	s_waitcnt vmcnt(19)
	v_lshlrev_b32_e32 v62, 16, v228
	v_and_b32_e32 v63, 0xffff0000, v228
	v_lshlrev_b32_e32 v58, 16, v229
	v_and_b32_e32 v59, 0xffff0000, v229
	v_lshlrev_b32_e32 v64, 16, v230
	v_and_b32_e32 v65, 0xffff0000, v230
	v_lshlrev_b32_e32 v60, 16, v231
	v_and_b32_e32 v61, 0xffff0000, v231
	v_pk_add_f32 v[56:57], v[56:57], v[58:59]
	v_pk_add_f32 v[54:55], v[54:55], v[62:63]
	v_pk_add_f32 v[58:59], v[52:53], v[60:61]
	v_pk_add_f32 v[60:61], v[50:51], v[64:65]
	v_cvt_pk_bf16_f32 v50, v54, v55
	v_cvt_pk_bf16_f32 v51, v56, v57
	v_cvt_pk_bf16_f32 v52, v60, v61
	v_cvt_pk_bf16_f32 v53, v58, v59
	global_store_dwordx4 v[72:73], v[50:53], off offset:256
	s_nop 1
	v_mul_f32_e32 v50, v55, v55
	v_mul_f32_e32 v51, v57, v57
	v_fmac_f32_e32 v50, v54, v54
	v_fmac_f32_e32 v51, v56, v56
	v_add_f32_e32 v50, v50, v51
	v_mul_f32_e32 v51, v61, v61
	v_fmac_f32_e32 v51, v60, v60
	v_add_f32_e32 v50, v51, v50
	v_mul_f32_e32 v51, v59, v59
	v_fmac_f32_e32 v51, v58, v58
	v_add_f32_e32 v50, v51, v50
	v_add_f32_e32 v0, v0, v50
	ds_bpermute_b32 v50, v153, v0
	s_waitcnt lgkmcnt(0)
	v_add_f32_e32 v0, v0, v50
	ds_bpermute_b32 v50, v152, v0
	s_and_saveexec_b64 s[22:23], s[2:3]
	s_cbranch_execz .LBB0_1042
	s_waitcnt lgkmcnt(0)
	v_add_f32_e32 v0, v0, v50
	v_fma_f32 v0, v0, s82, 0.5
	v_cvt_u32_f32_e32 v0, v0
	v_lshl_add_u64 v[50:51], v[66:67], 3, s[16:17]
	global_atomic_add_x2 v[50:51], v[0:1], off
.LBB0_1042:
	s_or_b64 exec, exec, s[22:23]
	s_waitcnt lgkmcnt(0)
	v_add_u32_e32 v50, 0x90, v146
	v_ashrrev_i32_e32 v51, 31, v50
	v_lshlrev_b64 v[52:53], 10, v[50:51]
	v_lshl_add_u64 v[52:53], v[52:53], 0, v[144:145]
	v_lshl_add_u64 v[56:57], v[52:53], 1, s[44:45]
	s_waitcnt vmcnt(20)
	v_lshlrev_b32_e32 v58, 16, v232
	v_and_b32_e32 v59, 0xffff0000, v232
	v_lshlrev_b32_e32 v52, 16, v233
	v_and_b32_e32 v53, 0xffff0000, v233
	v_lshlrev_b32_e32 v60, 16, v234
	v_and_b32_e32 v61, 0xffff0000, v234
	v_lshlrev_b32_e32 v54, 16, v235
	v_and_b32_e32 v55, 0xffff0000, v235
	v_pk_add_f32 v[48:49], v[48:49], v[52:53]
	v_pk_add_f32 v[46:47], v[46:47], v[58:59]
	v_pk_add_f32 v[52:53], v[44:45], v[54:55]
	v_pk_add_f32 v[54:55], v[42:43], v[60:61]
	v_cvt_pk_bf16_f32 v42, v46, v47
	v_cvt_pk_bf16_f32 v43, v48, v49
	v_cvt_pk_bf16_f32 v44, v54, v55
	v_cvt_pk_bf16_f32 v45, v52, v53
	global_store_dwordx4 v[56:57], v[42:45], off
	v_mul_f32_e32 v0, v47, v47
	v_fmac_f32_e32 v0, v46, v46
	v_mul_f32_e32 v42, v49, v49
	v_fmac_f32_e32 v42, v48, v48
	v_add_f32_e32 v0, v0, v42
	v_mul_f32_e32 v42, v55, v55
	v_fmac_f32_e32 v42, v54, v54
	v_add_f32_e32 v0, v42, v0
	v_mul_f32_e32 v42, v53, v53
	v_fmac_f32_e32 v42, v52, v52
	v_add_f32_e32 v0, v42, v0
	s_waitcnt vmcnt(20)
	v_lshlrev_b32_e32 v46, 16, v236
	v_and_b32_e32 v47, 0xffff0000, v236
	v_lshlrev_b32_e32 v42, 16, v237
	v_and_b32_e32 v43, 0xffff0000, v237
	v_lshlrev_b32_e32 v48, 16, v238
	v_and_b32_e32 v49, 0xffff0000, v238
	v_lshlrev_b32_e32 v44, 16, v239
	v_and_b32_e32 v45, 0xffff0000, v239
	v_pk_add_f32 v[40:41], v[40:41], v[42:43]
	v_pk_add_f32 v[38:39], v[38:39], v[46:47]
	v_pk_add_f32 v[42:43], v[36:37], v[44:45]
	v_pk_add_f32 v[44:45], v[34:35], v[48:49]
	v_cvt_pk_bf16_f32 v34, v38, v39
	v_cvt_pk_bf16_f32 v35, v40, v41
	v_cvt_pk_bf16_f32 v36, v44, v45
	v_cvt_pk_bf16_f32 v37, v42, v43
	global_store_dwordx4 v[56:57], v[34:37], off offset:256
	s_nop 1
	v_mul_f32_e32 v34, v39, v39
	v_mul_f32_e32 v35, v41, v41
	v_fmac_f32_e32 v34, v38, v38
	v_fmac_f32_e32 v35, v40, v40
	v_add_f32_e32 v34, v34, v35
	v_mul_f32_e32 v35, v45, v45
	v_fmac_f32_e32 v35, v44, v44
	v_add_f32_e32 v34, v35, v34
	v_mul_f32_e32 v35, v43, v43
	v_fmac_f32_e32 v35, v42, v42
	v_add_f32_e32 v34, v35, v34
	v_add_f32_e32 v0, v0, v34
	ds_bpermute_b32 v34, v153, v0
	s_waitcnt lgkmcnt(0)
	v_add_f32_e32 v0, v0, v34
	ds_bpermute_b32 v34, v152, v0
	s_and_saveexec_b64 s[22:23], s[2:3]
	s_cbranch_execz .LBB0_1044
	s_waitcnt lgkmcnt(0)
	v_add_f32_e32 v0, v0, v34
	v_fma_f32 v0, v0, s82, 0.5
	v_cvt_u32_f32_e32 v0, v0
	v_lshl_add_u64 v[34:35], v[50:51], 3, s[16:17]
	global_atomic_add_x2 v[34:35], v[0:1], off
.LBB0_1044:
	s_or_b64 exec, exec, s[22:23]
	s_waitcnt lgkmcnt(0)
	v_add_u32_e32 v34, 0xa0, v146
	v_ashrrev_i32_e32 v35, 31, v34
	v_lshlrev_b64 v[36:37], 10, v[34:35]
	v_lshl_add_u64 v[36:37], v[36:37], 0, v[144:145]
	v_lshl_add_u64 v[40:41], v[36:37], 1, s[44:45]
	s_waitcnt vmcnt(21)
	v_lshlrev_b32_e32 v42, 16, v240
	v_and_b32_e32 v43, 0xffff0000, v240
	v_lshlrev_b32_e32 v36, 16, v241
	v_and_b32_e32 v37, 0xffff0000, v241
	v_lshlrev_b32_e32 v44, 16, v242
	v_and_b32_e32 v45, 0xffff0000, v242
	v_lshlrev_b32_e32 v38, 16, v243
	v_and_b32_e32 v39, 0xffff0000, v243
	v_pk_add_f32 v[32:33], v[32:33], v[36:37]
	v_pk_add_f32 v[30:31], v[30:31], v[42:43]
	v_pk_add_f32 v[36:37], v[28:29], v[38:39]
	v_pk_add_f32 v[38:39], v[26:27], v[44:45]
	v_cvt_pk_bf16_f32 v26, v30, v31
	v_cvt_pk_bf16_f32 v27, v32, v33
	v_cvt_pk_bf16_f32 v28, v38, v39
	v_cvt_pk_bf16_f32 v29, v36, v37
	global_store_dwordx4 v[40:41], v[26:29], off
	v_mul_f32_e32 v0, v31, v31
	v_fmac_f32_e32 v0, v30, v30
	v_mul_f32_e32 v26, v33, v33
	v_fmac_f32_e32 v26, v32, v32
	v_add_f32_e32 v0, v0, v26
	v_mul_f32_e32 v26, v39, v39
	v_fmac_f32_e32 v26, v38, v38
	v_add_f32_e32 v0, v26, v0
	v_mul_f32_e32 v26, v37, v37
	v_fmac_f32_e32 v26, v36, v36
	v_add_f32_e32 v0, v26, v0
	s_waitcnt vmcnt(21)
	v_lshlrev_b32_e32 v30, 16, v244
	v_and_b32_e32 v31, 0xffff0000, v244
	v_lshlrev_b32_e32 v26, 16, v245
	v_and_b32_e32 v27, 0xffff0000, v245
	v_lshlrev_b32_e32 v32, 16, v246
	v_and_b32_e32 v33, 0xffff0000, v246
	v_lshlrev_b32_e32 v28, 16, v247
	v_and_b32_e32 v29, 0xffff0000, v247
	v_pk_add_f32 v[24:25], v[24:25], v[26:27]
	v_pk_add_f32 v[22:23], v[22:23], v[30:31]
	v_pk_add_f32 v[26:27], v[20:21], v[28:29]
	v_pk_add_f32 v[28:29], v[18:19], v[32:33]
	v_cvt_pk_bf16_f32 v18, v22, v23
	v_cvt_pk_bf16_f32 v19, v24, v25
	v_cvt_pk_bf16_f32 v20, v28, v29
	v_cvt_pk_bf16_f32 v21, v26, v27
	global_store_dwordx4 v[40:41], v[18:21], off offset:256
	s_nop 1
	v_mul_f32_e32 v18, v23, v23
	v_mul_f32_e32 v19, v25, v25
	v_fmac_f32_e32 v18, v22, v22
	v_fmac_f32_e32 v19, v24, v24
	v_add_f32_e32 v18, v18, v19
	v_mul_f32_e32 v19, v29, v29
	v_fmac_f32_e32 v19, v28, v28
	v_add_f32_e32 v18, v19, v18
	v_mul_f32_e32 v19, v27, v27
	v_fmac_f32_e32 v19, v26, v26
	v_add_f32_e32 v18, v19, v18
	v_add_f32_e32 v0, v0, v18
	ds_bpermute_b32 v18, v153, v0
	s_waitcnt lgkmcnt(0)
	v_add_f32_e32 v0, v0, v18
	ds_bpermute_b32 v18, v152, v0
	s_and_saveexec_b64 s[22:23], s[2:3]
	s_cbranch_execz .LBB0_1046
	s_waitcnt lgkmcnt(0)
	v_add_f32_e32 v0, v0, v18
	v_fma_f32 v0, v0, s82, 0.5
	v_cvt_u32_f32_e32 v0, v0
	v_lshl_add_u64 v[18:19], v[34:35], 3, s[16:17]
	global_atomic_add_x2 v[18:19], v[0:1], off
.LBB0_1046:
	s_or_b64 exec, exec, s[22:23]
	s_waitcnt lgkmcnt(0)
	v_add_u32_e32 v18, 0xb0, v146
	v_ashrrev_i32_e32 v19, 31, v18
	v_lshlrev_b64 v[20:21], 10, v[18:19]
	v_lshl_add_u64 v[20:21], v[20:21], 0, v[144:145]
	v_lshl_add_u64 v[24:25], v[20:21], 1, s[44:45]
	s_waitcnt vmcnt(19)
	v_lshlrev_b32_e32 v26, 16, v186
	v_and_b32_e32 v27, 0xffff0000, v186
	v_lshlrev_b32_e32 v20, 16, v187
	v_and_b32_e32 v21, 0xffff0000, v187
	v_lshlrev_b32_e32 v28, 16, v188
	v_and_b32_e32 v29, 0xffff0000, v188
	v_lshlrev_b32_e32 v22, 16, v189
	v_and_b32_e32 v23, 0xffff0000, v189
	v_pk_add_f32 v[16:17], v[16:17], v[20:21]
	v_pk_add_f32 v[14:15], v[14:15], v[26:27]
	v_pk_add_f32 v[20:21], v[12:13], v[22:23]
	v_pk_add_f32 v[22:23], v[10:11], v[28:29]
	v_cvt_pk_bf16_f32 v10, v14, v15
	v_cvt_pk_bf16_f32 v11, v16, v17
	v_cvt_pk_bf16_f32 v12, v22, v23
	v_cvt_pk_bf16_f32 v13, v20, v21
	global_store_dwordx4 v[24:25], v[10:13], off
	v_mul_f32_e32 v0, v15, v15
	v_fmac_f32_e32 v0, v14, v14
	v_mul_f32_e32 v10, v17, v17
	v_fmac_f32_e32 v10, v16, v16
	v_add_f32_e32 v0, v0, v10
	v_mul_f32_e32 v10, v23, v23
	v_fmac_f32_e32 v10, v22, v22
	v_add_f32_e32 v0, v10, v0
	v_mul_f32_e32 v10, v21, v21
	v_fmac_f32_e32 v10, v20, v20
	v_add_f32_e32 v0, v10, v0
	s_waitcnt vmcnt(19)
	v_lshlrev_b32_e32 v14, 16, v190
	v_and_b32_e32 v15, 0xffff0000, v190
	v_lshlrev_b32_e32 v10, 16, v191
	v_and_b32_e32 v11, 0xffff0000, v191
	v_lshlrev_b32_e32 v16, 16, v192
	v_and_b32_e32 v17, 0xffff0000, v192
	v_lshlrev_b32_e32 v12, 16, v193
	v_and_b32_e32 v13, 0xffff0000, v193
	v_pk_add_f32 v[8:9], v[8:9], v[10:11]
	v_pk_add_f32 v[6:7], v[6:7], v[14:15]
	v_pk_add_f32 v[10:11], v[4:5], v[12:13]
	v_pk_add_f32 v[12:13], v[2:3], v[16:17]
	v_cvt_pk_bf16_f32 v2, v6, v7
	v_cvt_pk_bf16_f32 v3, v8, v9
	v_cvt_pk_bf16_f32 v4, v12, v13
	v_cvt_pk_bf16_f32 v5, v10, v11
	global_store_dwordx4 v[24:25], v[2:5], off offset:256
	s_nop 1
	v_mul_f32_e32 v2, v7, v7
	v_mul_f32_e32 v3, v9, v9
	v_fmac_f32_e32 v2, v6, v6
	v_fmac_f32_e32 v3, v8, v8
	v_add_f32_e32 v2, v2, v3
	v_mul_f32_e32 v3, v13, v13
	v_fmac_f32_e32 v3, v12, v12
	v_add_f32_e32 v2, v3, v2
	v_mul_f32_e32 v3, v11, v11
	v_fmac_f32_e32 v3, v10, v10
	v_add_f32_e32 v2, v3, v2
	v_add_f32_e32 v0, v0, v2
	ds_bpermute_b32 v2, v153, v0
	s_waitcnt lgkmcnt(0)
	v_add_f32_e32 v0, v0, v2
	ds_bpermute_b32 v2, v152, v0
	s_and_saveexec_b64 s[22:23], s[2:3]
	s_cbranch_execz .LBB0_1048
	s_waitcnt lgkmcnt(0)
	v_add_f32_e32 v0, v0, v2
	v_fma_f32 v0, v0, s82, 0.5
	v_cvt_u32_f32_e32 v0, v0
	v_lshl_add_u64 v[4:5], v[18:19], 3, s[16:17]
	global_atomic_add_x2 v[4:5], v[0:1], off
